# code placement: K-loop heads and attention task loop aligned to 64 B (.p2align 6), on stack22
# baseline (speedup 1.0000x reference)
; template <class Epi, class Sched, bool ALIGN_EPI = false, bool SP2 = false>
; __device__ __forceinline__ void gemm_phase(PG8_LAS unsigned char* lds, const Gemm g, const Sched& S, const Epi& E) {
;     ...
;         const bool has_next = S.next(ui + 1, nxt);
;         const char* nA = has_next ? (const char*)g.A + (size_t)nxt.pm * tstep : cA; const char* nB = has_next ? (const char*)g.Bt + (size_t)nxt.pn * tstep : cB;
;         for (int t = 0; t < nt; t += 2) {
;             const bool last = (t == nt - 2);
;             const char* a1 = cA + (size_t)(t + 1) * kstep;
;             const char* a2 = last ? nA : cA + (size_t)(t + 2) * kstep; const char* b2 = last ? nB : cB + (size_t)(t + 2) * kstep;
;     ...
; #pragma unroll
;         for (int a = 0; a < 2; ++a)
; #pragma unroll
;             for (int b = 0; b < 2; ++b)
; #pragma unroll
;                 for (int m = 0; m < 4; ++m)
; #pragma unroll
;                     for (int n = 0; n < 2; ++n) acc[a][b][m][n] = (f32x4){0.f, 0.f, 0.f, 0.f};
;         cur = nxt; cA = nA; cB = nB; ++ui;
.LBB0_142:
	s_ashr_i32 s51, s50, 31
	s_lshl_b64 s[34:35], s[50:51], 19
	s_add_u32 s52, s60, s34
	s_addc_u32 s53, s61, s35
	s_and_b64 s[34:35], s[0:1], exec
	s_cselect_b32 s31, s53, s57
	s_cselect_b32 s33, s52, s56
	s_ashr_i32 s49, s48, 31
	s_lshl_b64 s[34:35], s[48:49], 19
	s_add_u32 s54, s3, s34
	s_addc_u32 s55, s10, s35
	s_and_b64 s[34:35], s[0:1], exec
	s_cselect_b32 s34, s55, s5
	s_cselect_b32 s35, s54, s4
	s_add_u32 s49, s4, 0x100
	s_addc_u32 s51, s5, 0
	s_add_u32 s4, s56, 0x40080
	v_mov_b32_e32 v0, 0
	s_addc_u32 s5, s57, 0
	s_mov_b32 s62, -2
	v_mov_b32_e32 v1, v0
	v_mov_b32_e32 v2, v0
	v_mov_b32_e32 v3, v0
	v_mov_b32_e32 v4, v0
	v_mov_b32_e32 v5, v0
	v_mov_b32_e32 v6, v0
	v_mov_b32_e32 v7, v0
	v_mov_b32_e32 v12, v0
	v_mov_b32_e32 v13, v0
	v_mov_b32_e32 v14, v0
	v_mov_b32_e32 v15, v0
	v_mov_b32_e32 v20, v0
	v_mov_b32_e32 v21, v0
	v_mov_b32_e32 v22, v0
	v_mov_b32_e32 v23, v0
	v_mov_b32_e32 v28, v0
	v_mov_b32_e32 v29, v0
	v_mov_b32_e32 v30, v0
	v_mov_b32_e32 v31, v0
	s_waitcnt vmcnt(0)
	v_mov_b32_e32 v36, v0
	v_mov_b32_e32 v37, v0
	v_mov_b32_e32 v38, v0
	v_mov_b32_e32 v39, v0
	v_mov_b32_e32 v44, v0
	v_mov_b32_e32 v45, v0
	v_mov_b32_e32 v46, v0
	v_mov_b32_e32 v47, v0
	v_mov_b32_e32 v52, v0
	v_mov_b32_e32 v53, v0
	v_mov_b32_e32 v54, v0
	v_mov_b32_e32 v55, v0
	v_mov_b32_e32 v8, v0
	v_mov_b32_e32 v9, v0
	v_mov_b32_e32 v10, v0
	v_mov_b32_e32 v11, v0
	v_mov_b32_e32 v16, v0
	v_mov_b32_e32 v17, v0
	v_mov_b32_e32 v18, v0
	v_mov_b32_e32 v19, v0
	v_mov_b32_e32 v24, v0
	v_mov_b32_e32 v25, v0
	v_mov_b32_e32 v26, v0
	v_mov_b32_e32 v27, v0
	v_mov_b32_e32 v32, v0
	v_mov_b32_e32 v33, v0
	v_mov_b32_e32 v34, v0
	v_mov_b32_e32 v35, v0
	v_mov_b32_e32 v40, v0
	v_mov_b32_e32 v41, v0
	v_mov_b32_e32 v42, v0
	v_mov_b32_e32 v43, v0
	v_mov_b32_e32 v48, v0
	v_mov_b32_e32 v49, v0
	v_mov_b32_e32 v50, v0
	v_mov_b32_e32 v51, v0
	v_mov_b32_e32 v56, v0
	v_mov_b32_e32 v57, v0
	v_mov_b32_e32 v58, v0
	v_mov_b32_e32 v59, v0
	v_mov_b32_e32 v60, v0
	v_mov_b32_e32 v61, v0
	v_mov_b32_e32 v62, v0
	v_mov_b32_e32 v63, v0
	v_mov_b32_e32 v64, v0
	v_mov_b32_e32 v65, v0
	v_mov_b32_e32 v66, v0
	v_mov_b32_e32 v67, v0
	v_mov_b32_e32 v68, v0
	v_mov_b32_e32 v69, v0
	v_mov_b32_e32 v70, v0
	v_mov_b32_e32 v71, v0
	v_mov_b32_e32 v80, v0
	v_mov_b32_e32 v81, v0
	v_mov_b32_e32 v82, v0
	v_mov_b32_e32 v83, v0
	v_mov_b32_e32 v84, v0
	v_mov_b32_e32 v85, v0
	v_mov_b32_e32 v86, v0
	v_mov_b32_e32 v87, v0
	v_mov_b32_e32 v96, v0
	v_mov_b32_e32 v97, v0
	v_mov_b32_e32 v98, v0
	v_mov_b32_e32 v99, v0
	v_mov_b32_e32 v100, v0
	v_mov_b32_e32 v101, v0
	v_mov_b32_e32 v102, v0
	v_mov_b32_e32 v103, v0
	v_mov_b32_e32 v112, v0
	v_mov_b32_e32 v113, v0
	v_mov_b32_e32 v114, v0
	v_mov_b32_e32 v115, v0
	v_mov_b32_e32 v116, v0
	v_mov_b32_e32 v117, v0
	v_mov_b32_e32 v118, v0
	v_mov_b32_e32 v119, v0
	v_mov_b32_e32 v72, v0
	v_mov_b32_e32 v73, v0
	v_mov_b32_e32 v74, v0
	v_mov_b32_e32 v75, v0
	v_mov_b32_e32 v76, v0
	v_mov_b32_e32 v77, v0
	v_mov_b32_e32 v78, v0
	v_mov_b32_e32 v79, v0
	v_mov_b32_e32 v88, v0
	v_mov_b32_e32 v89, v0
	v_mov_b32_e32 v90, v0
	v_mov_b32_e32 v91, v0
	v_mov_b32_e32 v92, v0
	v_mov_b32_e32 v93, v0
	v_mov_b32_e32 v94, v0
	v_mov_b32_e32 v95, v0
	v_mov_b32_e32 v104, v0
	v_mov_b32_e32 v105, v0
	v_mov_b32_e32 v106, v0
	v_mov_b32_e32 v107, v0
	v_mov_b32_e32 v108, v0
	v_mov_b32_e32 v109, v0
	v_mov_b32_e32 v110, v0
	v_mov_b32_e32 v111, v0
	v_mov_b32_e32 v120, v0
	v_mov_b32_e32 v121, v0
	v_mov_b32_e32 v122, v0
	v_mov_b32_e32 v123, v0
	v_mov_b32_e32 v124, v0
	v_mov_b32_e32 v125, v0
	v_mov_b32_e32 v126, v0
	v_mov_b32_e32 v127, v0
	.p2align 6

; template <class Epi, class Sched, bool ALIGN_EPI = false, bool SP2 = false>
; __device__ __forceinline__ void gemm_phase(PG8_LAS unsigned char* lds, const Gemm g, const Sched& S, const Epi& E) {
;     ...
;         const bool has_next = S.next(ui + 1, nxt);
;         const char* nA = has_next ? (const char*)g.A + (size_t)nxt.pm * tstep : cA; const char* nB = has_next ? (const char*)g.Bt + (size_t)nxt.pn * tstep : cB;
;         for (int t = 0; t < nt; t += 2) {
;             const bool last = (t == nt - 2);
;             const char* a1 = cA + (size_t)(t + 1) * kstep;
;             const char* a2 = last ? nA : cA + (size_t)(t + 2) * kstep; const char* b2 = last ? nB : cB + (size_t)(t + 2) * kstep;
;     ...
; #pragma unroll
;         for (int a = 0; a < 2; ++a)
; #pragma unroll
;             for (int b = 0; b < 2; ++b)
; #pragma unroll
;                 for (int m = 0; m < 4; ++m)
; #pragma unroll
;                     for (int n = 0; n < 2; ++n) acc[a][b][m][n] = (f32x4){0.f, 0.f, 0.f, 0.f};
;         cur = nxt; cA = nA; cB = nB; ++ui;
.LBB0_264:
	s_ashr_i32 s49, s48, 31
	s_lshl_b64 s[20:21], s[48:49], 19
	s_add_u32 s50, s60, s20
	s_addc_u32 s51, s61, s21
	s_and_b64 s[20:21], s[38:39], exec
	s_cselect_b32 s11, s51, s17
	s_cselect_b32 s14, s50, s16
	s_ashr_i32 s47, s46, 31
	s_lshl_b64 s[20:21], s[46:47], 19
	s_add_u32 s52, s34, s20
	s_addc_u32 s53, s35, s21
	s_and_b64 s[20:21], s[38:39], exec
	s_cselect_b32 s20, s53, s1
	s_cselect_b32 s21, s52, s0
	s_add_u32 s22, s0, 0x100
	s_addc_u32 s23, s1, 0
	s_add_u32 s0, s16, 0x40080
	v_mov_b32_e32 v0, 0
	s_addc_u32 s1, s17, 0
	s_mov_b32 s24, -2
	v_mov_b32_e32 v1, v0
	v_mov_b32_e32 v2, v0
	v_mov_b32_e32 v3, v0
	v_mov_b32_e32 v4, v0
	v_mov_b32_e32 v5, v0
	v_mov_b32_e32 v6, v0
	v_mov_b32_e32 v7, v0
	s_waitcnt lgkmcnt(0)
	v_mov_b32_e32 v16, v0
	v_mov_b32_e32 v17, v0
	v_mov_b32_e32 v18, v0
	v_mov_b32_e32 v19, v0
	v_mov_b32_e32 v20, v0
	v_mov_b32_e32 v21, v0
	v_mov_b32_e32 v22, v0
	v_mov_b32_e32 v23, v0
	v_mov_b32_e32 v32, v0
	v_mov_b32_e32 v33, v0
	v_mov_b32_e32 v34, v0
	v_mov_b32_e32 v35, v0
	v_mov_b32_e32 v36, v0
	v_mov_b32_e32 v37, v0
	v_mov_b32_e32 v38, v0
	v_mov_b32_e32 v39, v0
	v_mov_b32_e32 v48, v0
	v_mov_b32_e32 v49, v0
	v_mov_b32_e32 v50, v0
	v_mov_b32_e32 v51, v0
	v_mov_b32_e32 v52, v0
	v_mov_b32_e32 v53, v0
	v_mov_b32_e32 v54, v0
	v_mov_b32_e32 v55, v0
	v_mov_b32_e32 v8, v0
	v_mov_b32_e32 v9, v0
	v_mov_b32_e32 v10, v0
	v_mov_b32_e32 v11, v0
	v_mov_b32_e32 v12, v0
	v_mov_b32_e32 v13, v0
	v_mov_b32_e32 v14, v0
	v_mov_b32_e32 v15, v0
	v_mov_b32_e32 v24, v0
	v_mov_b32_e32 v25, v0
	v_mov_b32_e32 v26, v0
	v_mov_b32_e32 v27, v0
	v_mov_b32_e32 v28, v0
	v_mov_b32_e32 v29, v0
	v_mov_b32_e32 v30, v0
	v_mov_b32_e32 v31, v0
	v_mov_b32_e32 v40, v0
	v_mov_b32_e32 v41, v0
	v_mov_b32_e32 v42, v0
	v_mov_b32_e32 v43, v0
	v_mov_b32_e32 v44, v0
	v_mov_b32_e32 v45, v0
	v_mov_b32_e32 v46, v0
	v_mov_b32_e32 v47, v0
	v_mov_b32_e32 v56, v0
	v_mov_b32_e32 v57, v0
	v_mov_b32_e32 v58, v0
	v_mov_b32_e32 v59, v0
	v_mov_b32_e32 v60, v0
	v_mov_b32_e32 v61, v0
	v_mov_b32_e32 v62, v0
	v_mov_b32_e32 v63, v0
	v_mov_b32_e32 v64, v0
	v_mov_b32_e32 v65, v0
	v_mov_b32_e32 v66, v0
	v_mov_b32_e32 v67, v0
	v_mov_b32_e32 v68, v0
	v_mov_b32_e32 v69, v0
	v_mov_b32_e32 v70, v0
	v_mov_b32_e32 v71, v0
	v_mov_b32_e32 v80, v0
	v_mov_b32_e32 v81, v0
	v_mov_b32_e32 v82, v0
	v_mov_b32_e32 v83, v0
	v_mov_b32_e32 v84, v0
	v_mov_b32_e32 v85, v0
	v_mov_b32_e32 v86, v0
	v_mov_b32_e32 v87, v0
	v_mov_b32_e32 v96, v0
	v_mov_b32_e32 v97, v0
	v_mov_b32_e32 v98, v0
	v_mov_b32_e32 v99, v0
	v_mov_b32_e32 v100, v0
	v_mov_b32_e32 v101, v0
	v_mov_b32_e32 v102, v0
	v_mov_b32_e32 v103, v0
	v_mov_b32_e32 v112, v0
	v_mov_b32_e32 v113, v0
	v_mov_b32_e32 v114, v0
	v_mov_b32_e32 v115, v0
	v_mov_b32_e32 v116, v0
	v_mov_b32_e32 v117, v0
	v_mov_b32_e32 v118, v0
	v_mov_b32_e32 v119, v0
	v_mov_b32_e32 v72, v0
	v_mov_b32_e32 v73, v0
	v_mov_b32_e32 v74, v0
	v_mov_b32_e32 v75, v0
	v_mov_b32_e32 v76, v0
	v_mov_b32_e32 v77, v0
	v_mov_b32_e32 v78, v0
	v_mov_b32_e32 v79, v0
	v_mov_b32_e32 v88, v0
	v_mov_b32_e32 v89, v0
	v_mov_b32_e32 v90, v0
	v_mov_b32_e32 v91, v0
	v_mov_b32_e32 v92, v0
	v_mov_b32_e32 v93, v0
	v_mov_b32_e32 v94, v0
	v_mov_b32_e32 v95, v0
	v_mov_b32_e32 v104, v0
	v_mov_b32_e32 v105, v0
	v_mov_b32_e32 v106, v0
	v_mov_b32_e32 v107, v0
	v_mov_b32_e32 v108, v0
	v_mov_b32_e32 v109, v0
	v_mov_b32_e32 v110, v0
	v_mov_b32_e32 v111, v0
	v_mov_b32_e32 v120, v0
	v_mov_b32_e32 v121, v0
	v_mov_b32_e32 v122, v0
	v_mov_b32_e32 v123, v0
	v_mov_b32_e32 v124, v0
	v_mov_b32_e32 v125, v0
	v_mov_b32_e32 v126, v0
	v_mov_b32_e32 v127, v0
	.p2align 6

; __device__ __forceinline__ void attn_phase(const Args& A, LAS unsigned char* lds, int tid, int lane, int wave, int bx, int G) {
;     ...
; #pragma unroll 1
;     for (int kstep = 0; AT_VALID(kstep); ++kstep) {
;         const int item = AT_ITEM(kstep), span = item & 15, bh = item >> 4, pos0 = span * 512;
; #pragma unroll 1
;         for (int i = 0; i < 6; ++i) {
;             At32 nxt;
;             if (i < 5) { AT_TASK(nxt, item, i + 1); } else { const int ni = AT_VALID(kstep + 1) ? AT_ITEM(kstep + 1) : item; AT_TASK(nxt, ni, 0); }
;             at_task32(A, cur, nxt, qf, kf, lds, vst, lane);
;             cur = nxt;
;             if (i & 1) __syncthreads();
;         }
.LBB0_395:
	s_andn2_b64 vcc, exec, s[6:7]
	s_cbranch_vccz .LBB0_393
	s_branch .LBB0_394
	.p2align 6

; template <class Epi, class Sched, bool ALIGN_EPI = false, bool SP2 = false>
; __device__ __forceinline__ void gemm_phase(PG8_LAS unsigned char* lds, const Gemm g, const Sched& S, const Epi& E) {
;     ...
;         const bool has_next = S.next(ui + 1, nxt);
;         const char* nA = has_next ? (const char*)g.A + (size_t)nxt.pm * tstep : cA; const char* nB = has_next ? (const char*)g.Bt + (size_t)nxt.pn * tstep : cB;
;         for (int t = 0; t < nt; t += 2) {
;             const bool last = (t == nt - 2);
;             const char* a1 = cA + (size_t)(t + 1) * kstep;
;             const char* a2 = last ? nA : cA + (size_t)(t + 2) * kstep; const char* b2 = last ? nB : cB + (size_t)(t + 2) * kstep;
;     ...
; #pragma unroll
;         for (int a = 0; a < 2; ++a)
; #pragma unroll
;             for (int b = 0; b < 2; ++b)
; #pragma unroll
;                 for (int m = 0; m < 4; ++m)
; #pragma unroll
;                     for (int n = 0; n < 2; ++n) acc[a][b][m][n] = (f32x4){0.f, 0.f, 0.f, 0.f};
;         cur = nxt; cA = nA; cB = nB; ++ui;
.LBB0_557:
	s_ashr_i32 s43, s42, 31
	s_lshl_b64 s[34:35], s[42:43], 19
	s_add_u32 s44, s2, s34
	s_addc_u32 s45, s3, s35
	s_and_b64 s[34:35], s[4:5], exec
	s_cselect_b32 s33, s45, s51
	s_cselect_b32 s34, s44, s50
	s_ashr_i32 s41, s40, 31
	s_lshl_b64 s[46:47], s[40:41], 19
	s_add_u32 s46, s10, s46
	s_addc_u32 s47, s11, s47
	s_and_b64 s[52:53], s[4:5], exec
	s_cselect_b32 s35, s47, s49
	s_cselect_b32 s41, s46, s48
	s_add_u32 s43, s48, 0x100
	s_addc_u32 s54, s49, 0
	s_add_u32 s48, s50, 0x40080
	v_mov_b32_e32 v0, 0
	s_addc_u32 s49, s51, 0
	s_mov_b32 s55, -2
	s_waitcnt lgkmcnt(0)
	v_mov_b32_e32 v1, v0
	v_mov_b32_e32 v2, v0
	v_mov_b32_e32 v3, v0
	v_mov_b32_e32 v4, v0
	v_mov_b32_e32 v5, v0
	v_mov_b32_e32 v6, v0
	v_mov_b32_e32 v7, v0
	v_mov_b32_e32 v16, v0
	v_mov_b32_e32 v17, v0
	v_mov_b32_e32 v18, v0
	v_mov_b32_e32 v19, v0
	v_mov_b32_e32 v20, v0
	v_mov_b32_e32 v21, v0
	v_mov_b32_e32 v22, v0
	v_mov_b32_e32 v23, v0
	v_mov_b32_e32 v32, v0
	v_mov_b32_e32 v33, v0
	v_mov_b32_e32 v34, v0
	v_mov_b32_e32 v35, v0
	v_mov_b32_e32 v36, v0
	v_mov_b32_e32 v37, v0
	v_mov_b32_e32 v38, v0
	v_mov_b32_e32 v39, v0
	v_mov_b32_e32 v48, v0
	v_mov_b32_e32 v49, v0
	v_mov_b32_e32 v50, v0
	v_mov_b32_e32 v51, v0
	v_mov_b32_e32 v52, v0
	v_mov_b32_e32 v53, v0
	v_mov_b32_e32 v54, v0
	v_mov_b32_e32 v55, v0
	v_mov_b32_e32 v8, v0
	v_mov_b32_e32 v9, v0
	v_mov_b32_e32 v10, v0
	v_mov_b32_e32 v11, v0
	v_mov_b32_e32 v12, v0
	v_mov_b32_e32 v13, v0
	v_mov_b32_e32 v14, v0
	v_mov_b32_e32 v15, v0
	v_mov_b32_e32 v24, v0
	v_mov_b32_e32 v25, v0
	v_mov_b32_e32 v26, v0
	v_mov_b32_e32 v27, v0
	v_mov_b32_e32 v28, v0
	v_mov_b32_e32 v29, v0
	v_mov_b32_e32 v30, v0
	v_mov_b32_e32 v31, v0
	v_mov_b32_e32 v40, v0
	v_mov_b32_e32 v41, v0
	v_mov_b32_e32 v42, v0
	v_mov_b32_e32 v43, v0
	v_mov_b32_e32 v44, v0
	v_mov_b32_e32 v45, v0
	v_mov_b32_e32 v46, v0
	v_mov_b32_e32 v47, v0
	v_mov_b32_e32 v56, v0
	v_mov_b32_e32 v57, v0
	v_mov_b32_e32 v58, v0
	v_mov_b32_e32 v59, v0
	v_mov_b32_e32 v60, v0
	v_mov_b32_e32 v61, v0
	v_mov_b32_e32 v62, v0
	v_mov_b32_e32 v63, v0
	v_mov_b32_e32 v64, v0
	v_mov_b32_e32 v65, v0
	v_mov_b32_e32 v66, v0
	v_mov_b32_e32 v67, v0
	v_mov_b32_e32 v68, v0
	v_mov_b32_e32 v69, v0
	v_mov_b32_e32 v70, v0
	v_mov_b32_e32 v71, v0
	v_mov_b32_e32 v80, v0
	v_mov_b32_e32 v81, v0
	v_mov_b32_e32 v82, v0
	v_mov_b32_e32 v83, v0
	v_mov_b32_e32 v84, v0
	v_mov_b32_e32 v85, v0
	v_mov_b32_e32 v86, v0
	v_mov_b32_e32 v87, v0
	v_mov_b32_e32 v96, v0
	v_mov_b32_e32 v97, v0
	v_mov_b32_e32 v98, v0
	v_mov_b32_e32 v99, v0
	v_mov_b32_e32 v100, v0
	v_mov_b32_e32 v101, v0
	v_mov_b32_e32 v102, v0
	v_mov_b32_e32 v103, v0
	v_mov_b32_e32 v136, v0
	v_mov_b32_e32 v137, v0
	v_mov_b32_e32 v138, v0
	v_mov_b32_e32 v139, v0
	v_mov_b32_e32 v140, v0
	v_mov_b32_e32 v141, v0
	v_mov_b32_e32 v142, v0
	v_mov_b32_e32 v143, v0
	v_mov_b32_e32 v72, v0
	v_mov_b32_e32 v73, v0
	v_mov_b32_e32 v74, v0
	v_mov_b32_e32 v75, v0
	v_mov_b32_e32 v76, v0
	v_mov_b32_e32 v77, v0
	v_mov_b32_e32 v78, v0
	v_mov_b32_e32 v79, v0
	v_mov_b32_e32 v88, v0
	v_mov_b32_e32 v89, v0
	v_mov_b32_e32 v90, v0
	v_mov_b32_e32 v91, v0
	v_mov_b32_e32 v92, v0
	v_mov_b32_e32 v93, v0
	v_mov_b32_e32 v94, v0
	v_mov_b32_e32 v95, v0
	v_mov_b32_e32 v104, v0
	v_mov_b32_e32 v105, v0
	v_mov_b32_e32 v106, v0
	v_mov_b32_e32 v107, v0
	v_mov_b32_e32 v108, v0
	v_mov_b32_e32 v109, v0
	v_mov_b32_e32 v110, v0
	v_mov_b32_e32 v111, v0
	v_mov_b32_e32 v144, v0
	v_mov_b32_e32 v145, v0
	v_mov_b32_e32 v146, v0
	v_mov_b32_e32 v147, v0
	v_mov_b32_e32 v148, v0
	v_mov_b32_e32 v149, v0
	v_mov_b32_e32 v150, v0
	v_mov_b32_e32 v151, v0
	.p2align 6

; template <class Epi, class Sched, bool ALIGN_EPI = false, bool SP2 = false>
; __device__ __forceinline__ void gemm_phase(PG8_LAS unsigned char* lds, const Gemm g, const Sched& S, const Epi& E) {
;     ...
;         const bool has_next = S.next(ui + 1, nxt);
;         const char* nA = has_next ? (const char*)g.A + (size_t)nxt.pm * tstep : cA; const char* nB = has_next ? (const char*)g.Bt + (size_t)nxt.pn * tstep : cB;
;         for (int t = 0; t < nt; t += 2) {
;             const bool last = (t == nt - 2);
;             const char* a1 = cA + (size_t)(t + 1) * kstep;
;             const char* a2 = last ? nA : cA + (size_t)(t + 2) * kstep; const char* b2 = last ? nB : cB + (size_t)(t + 2) * kstep;
;     ...
; #pragma unroll
;         for (int a = 0; a < 2; ++a)
; #pragma unroll
;             for (int b = 0; b < 2; ++b)
; #pragma unroll
;                 for (int m = 0; m < 4; ++m)
; #pragma unroll
;                     for (int n = 0; n < 2; ++n) acc[a][b][m][n] = (f32x4){0.f, 0.f, 0.f, 0.f};
;         cur = nxt; cA = nA; cB = nB; ++ui;
.LBB0_658:
	s_ashr_i32 s41, s40, 31
	s_lshl_b64 s[34:35], s[40:41], 19
	s_add_u32 s42, s2, s34
	s_addc_u32 s43, s3, s35
	s_and_b64 s[34:35], s[0:1], exec
	s_cselect_b32 s33, s43, s49
	s_cselect_b32 s34, s42, s48
	s_ashr_i32 s27, s26, 31
	s_lshl_b64 s[44:45], s[26:27], 19
	s_add_u32 s44, s10, s44
	s_addc_u32 s45, s11, s45
	s_and_b64 s[50:51], s[0:1], exec
	s_cselect_b32 s27, s45, s47
	s_cselect_b32 s35, s44, s46
	s_add_u32 s41, s46, 0x100
	s_addc_u32 s52, s47, 0
	s_add_u32 s46, s48, 0x40080
	v_mov_b32_e32 v0, 0
	s_addc_u32 s47, s49, 0
	s_mov_b32 s53, -2
	v_mov_b32_e32 v1, v0
	v_mov_b32_e32 v2, v0
	v_mov_b32_e32 v3, v0
	v_mov_b32_e32 v4, v0
	v_mov_b32_e32 v5, v0
	v_mov_b32_e32 v6, v0
	v_mov_b32_e32 v7, v0
	v_mov_b32_e32 v16, v0
	v_mov_b32_e32 v17, v0
	v_mov_b32_e32 v18, v0
	v_mov_b32_e32 v19, v0
	v_mov_b32_e32 v20, v0
	v_mov_b32_e32 v21, v0
	v_mov_b32_e32 v22, v0
	v_mov_b32_e32 v23, v0
	v_mov_b32_e32 v32, v0
	v_mov_b32_e32 v33, v0
	v_mov_b32_e32 v34, v0
	v_mov_b32_e32 v35, v0
	v_mov_b32_e32 v36, v0
	v_mov_b32_e32 v37, v0
	v_mov_b32_e32 v38, v0
	v_mov_b32_e32 v39, v0
	v_mov_b32_e32 v48, v0
	v_mov_b32_e32 v49, v0
	v_mov_b32_e32 v50, v0
	v_mov_b32_e32 v51, v0
	v_mov_b32_e32 v52, v0
	v_mov_b32_e32 v53, v0
	v_mov_b32_e32 v54, v0
	v_mov_b32_e32 v55, v0
	v_mov_b32_e32 v8, v0
	v_mov_b32_e32 v9, v0
	v_mov_b32_e32 v10, v0
	v_mov_b32_e32 v11, v0
	v_mov_b32_e32 v12, v0
	v_mov_b32_e32 v13, v0
	v_mov_b32_e32 v14, v0
	v_mov_b32_e32 v15, v0
	v_mov_b32_e32 v24, v0
	v_mov_b32_e32 v25, v0
	v_mov_b32_e32 v26, v0
	v_mov_b32_e32 v27, v0
	v_mov_b32_e32 v28, v0
	v_mov_b32_e32 v29, v0
	v_mov_b32_e32 v30, v0
	v_mov_b32_e32 v31, v0
	v_mov_b32_e32 v40, v0
	v_mov_b32_e32 v41, v0
	v_mov_b32_e32 v42, v0
	v_mov_b32_e32 v43, v0
	v_mov_b32_e32 v44, v0
	v_mov_b32_e32 v45, v0
	v_mov_b32_e32 v46, v0
	v_mov_b32_e32 v47, v0
	v_mov_b32_e32 v56, v0
	v_mov_b32_e32 v57, v0
	v_mov_b32_e32 v58, v0
	v_mov_b32_e32 v59, v0
	v_mov_b32_e32 v60, v0
	v_mov_b32_e32 v61, v0
	v_mov_b32_e32 v62, v0
	v_mov_b32_e32 v63, v0
	v_mov_b32_e32 v64, v0
	v_mov_b32_e32 v65, v0
	v_mov_b32_e32 v66, v0
	v_mov_b32_e32 v67, v0
	v_mov_b32_e32 v68, v0
	v_mov_b32_e32 v69, v0
	v_mov_b32_e32 v70, v0
	v_mov_b32_e32 v71, v0
	v_mov_b32_e32 v80, v0
	v_mov_b32_e32 v81, v0
	v_mov_b32_e32 v82, v0
	v_mov_b32_e32 v83, v0
	v_mov_b32_e32 v84, v0
	v_mov_b32_e32 v85, v0
	v_mov_b32_e32 v86, v0
	v_mov_b32_e32 v87, v0
	v_mov_b32_e32 v96, v0
	v_mov_b32_e32 v97, v0
	v_mov_b32_e32 v98, v0
	v_mov_b32_e32 v99, v0
	v_mov_b32_e32 v100, v0
	v_mov_b32_e32 v101, v0
	v_mov_b32_e32 v102, v0
	v_mov_b32_e32 v103, v0
	v_mov_b32_e32 v112, v0
	v_mov_b32_e32 v113, v0
	v_mov_b32_e32 v114, v0
	v_mov_b32_e32 v115, v0
	v_mov_b32_e32 v116, v0
	v_mov_b32_e32 v117, v0
	v_mov_b32_e32 v118, v0
	v_mov_b32_e32 v119, v0
	v_mov_b32_e32 v72, v0
	v_mov_b32_e32 v73, v0
	v_mov_b32_e32 v74, v0
	v_mov_b32_e32 v75, v0
	v_mov_b32_e32 v76, v0
	v_mov_b32_e32 v77, v0
	v_mov_b32_e32 v78, v0
	v_mov_b32_e32 v79, v0
	v_mov_b32_e32 v88, v0
	v_mov_b32_e32 v89, v0
	v_mov_b32_e32 v90, v0
	v_mov_b32_e32 v91, v0
	v_mov_b32_e32 v92, v0
	v_mov_b32_e32 v93, v0
	v_mov_b32_e32 v94, v0
	v_mov_b32_e32 v95, v0
	v_mov_b32_e32 v104, v0
	v_mov_b32_e32 v105, v0
	v_mov_b32_e32 v106, v0
	v_mov_b32_e32 v107, v0
	v_mov_b32_e32 v108, v0
	v_mov_b32_e32 v109, v0
	v_mov_b32_e32 v110, v0
	v_mov_b32_e32 v111, v0
	v_mov_b32_e32 v120, v0
	v_mov_b32_e32 v121, v0
	v_mov_b32_e32 v122, v0
	v_mov_b32_e32 v123, v0
	v_mov_b32_e32 v124, v0
	v_mov_b32_e32 v125, v0
	v_mov_b32_e32 v126, v0
	v_mov_b32_e32 v127, v0
	.p2align 6

; template <class Epi, class Sched, bool ALIGN_EPI = false, bool SP2 = false>
; __device__ __forceinline__ void gemm_phase(PG8_LAS unsigned char* lds, const Gemm g, const Sched& S, const Epi& E) {
;     ...
;         const bool has_next = S.next(ui + 1, nxt);
;         const char* nA = has_next ? (const char*)g.A + (size_t)nxt.pm * tstep : cA; const char* nB = has_next ? (const char*)g.Bt + (size_t)nxt.pn * tstep : cB;
;         for (int t = 0; t < nt; t += 2) {
;             const bool last = (t == nt - 2);
;             const char* a1 = cA + (size_t)(t + 1) * kstep;
;             const char* a2 = last ? nA : cA + (size_t)(t + 2) * kstep; const char* b2 = last ? nB : cB + (size_t)(t + 2) * kstep;
;     ...
; #pragma unroll
;         for (int a = 0; a < 2; ++a)
; #pragma unroll
;             for (int b = 0; b < 2; ++b)
; #pragma unroll
;                 for (int m = 0; m < 4; ++m)
; #pragma unroll
;                     for (int n = 0; n < 2; ++n) acc[a][b][m][n] = (f32x4){0.f, 0.f, 0.f, 0.f};
;         cur = nxt; cA = nA; cB = nB; ++ui;
.LBB0_743:
	s_ashr_i32 s51, s50, 31
	s_lshl_b64 s[34:35], s[50:51], 21
	s_add_u32 s52, s2, s34
	s_addc_u32 s53, s3, s35
	s_and_b64 s[34:35], s[6:7], exec
	s_cselect_b32 s33, s53, s39
	s_cselect_b32 s34, s52, s38
	s_ashr_i32 s49, s48, 31
	s_lshl_b64 s[54:55], s[48:49], 21
	s_add_u32 s54, s10, s54
	s_addc_u32 s55, s11, s55
	s_and_b64 s[56:57], s[6:7], exec
	s_cselect_b32 s35, s55, s5
	s_cselect_b32 s49, s54, s4
	s_add_u32 s51, s4, 0x100
	s_addc_u32 s58, s5, 0
	s_add_u32 s4, s38, 0x100080
	v_mov_b32_e32 v0, 0
	s_addc_u32 s5, s39, 0
	s_mov_b32 s59, -2
	s_waitcnt lgkmcnt(0)
	v_mov_b32_e32 v1, v0
	v_mov_b32_e32 v2, v0
	v_mov_b32_e32 v3, v0
	v_mov_b32_e32 v4, v0
	v_mov_b32_e32 v5, v0
	v_mov_b32_e32 v6, v0
	v_mov_b32_e32 v7, v0
	v_mov_b32_e32 v16, v0
	v_mov_b32_e32 v17, v0
	v_mov_b32_e32 v18, v0
	v_mov_b32_e32 v19, v0
	v_mov_b32_e32 v20, v0
	v_mov_b32_e32 v21, v0
	v_mov_b32_e32 v22, v0
	v_mov_b32_e32 v23, v0
	v_mov_b32_e32 v32, v0
	v_mov_b32_e32 v33, v0
	v_mov_b32_e32 v34, v0
	v_mov_b32_e32 v35, v0
	v_mov_b32_e32 v36, v0
	v_mov_b32_e32 v37, v0
	v_mov_b32_e32 v38, v0
	v_mov_b32_e32 v39, v0
	v_mov_b32_e32 v48, v0
	v_mov_b32_e32 v49, v0
	v_mov_b32_e32 v50, v0
	v_mov_b32_e32 v51, v0
	v_mov_b32_e32 v52, v0
	v_mov_b32_e32 v53, v0
	v_mov_b32_e32 v54, v0
	v_mov_b32_e32 v55, v0
	v_mov_b32_e32 v8, v0
	v_mov_b32_e32 v9, v0
	v_mov_b32_e32 v10, v0
	v_mov_b32_e32 v11, v0
	v_mov_b32_e32 v12, v0
	v_mov_b32_e32 v13, v0
	v_mov_b32_e32 v14, v0
	v_mov_b32_e32 v15, v0
	v_mov_b32_e32 v24, v0
	v_mov_b32_e32 v25, v0
	v_mov_b32_e32 v26, v0
	v_mov_b32_e32 v27, v0
	v_mov_b32_e32 v28, v0
	v_mov_b32_e32 v29, v0
	v_mov_b32_e32 v30, v0
	v_mov_b32_e32 v31, v0
	v_mov_b32_e32 v40, v0
	v_mov_b32_e32 v41, v0
	v_mov_b32_e32 v42, v0
	v_mov_b32_e32 v43, v0
	v_mov_b32_e32 v44, v0
	v_mov_b32_e32 v45, v0
	v_mov_b32_e32 v46, v0
	v_mov_b32_e32 v47, v0
	v_mov_b32_e32 v56, v0
	v_mov_b32_e32 v57, v0
	v_mov_b32_e32 v58, v0
	v_mov_b32_e32 v59, v0
	v_mov_b32_e32 v60, v0
	v_mov_b32_e32 v61, v0
	v_mov_b32_e32 v62, v0
	v_mov_b32_e32 v63, v0
	v_mov_b32_e32 v64, v0
	v_mov_b32_e32 v65, v0
	v_mov_b32_e32 v66, v0
	v_mov_b32_e32 v67, v0
	v_mov_b32_e32 v68, v0
	v_mov_b32_e32 v69, v0
	v_mov_b32_e32 v70, v0
	v_mov_b32_e32 v71, v0
	v_mov_b32_e32 v80, v0
	v_mov_b32_e32 v81, v0
	v_mov_b32_e32 v82, v0
	v_mov_b32_e32 v83, v0
	v_mov_b32_e32 v84, v0
	v_mov_b32_e32 v85, v0
	v_mov_b32_e32 v86, v0
	v_mov_b32_e32 v87, v0
	v_mov_b32_e32 v96, v0
	v_mov_b32_e32 v97, v0
	v_mov_b32_e32 v98, v0
	v_mov_b32_e32 v99, v0
	v_mov_b32_e32 v100, v0
	v_mov_b32_e32 v101, v0
	v_mov_b32_e32 v102, v0
	v_mov_b32_e32 v103, v0
	v_mov_b32_e32 v112, v0
	v_mov_b32_e32 v113, v0
	v_mov_b32_e32 v114, v0
	v_mov_b32_e32 v115, v0
	v_mov_b32_e32 v116, v0
	v_mov_b32_e32 v117, v0
	v_mov_b32_e32 v118, v0
	v_mov_b32_e32 v119, v0
	v_mov_b32_e32 v72, v0
	v_mov_b32_e32 v73, v0
	v_mov_b32_e32 v74, v0
	v_mov_b32_e32 v75, v0
	v_mov_b32_e32 v76, v0
	v_mov_b32_e32 v77, v0
	v_mov_b32_e32 v78, v0
	v_mov_b32_e32 v79, v0
	v_mov_b32_e32 v88, v0
	v_mov_b32_e32 v89, v0
	v_mov_b32_e32 v90, v0
	v_mov_b32_e32 v91, v0
	v_mov_b32_e32 v92, v0
	v_mov_b32_e32 v93, v0
	v_mov_b32_e32 v94, v0
	v_mov_b32_e32 v95, v0
	v_mov_b32_e32 v104, v0
	v_mov_b32_e32 v105, v0
	v_mov_b32_e32 v106, v0
	v_mov_b32_e32 v107, v0
	v_mov_b32_e32 v108, v0
	v_mov_b32_e32 v109, v0
	v_mov_b32_e32 v110, v0
	v_mov_b32_e32 v111, v0
	v_mov_b32_e32 v124, v0
	v_mov_b32_e32 v125, v0
	v_mov_b32_e32 v126, v0
	v_mov_b32_e32 v127, v0
	v_mov_b32_e32 v128, v0
	v_mov_b32_e32 v129, v0
	v_mov_b32_e32 v130, v0
	v_mov_b32_e32 v131, v0
	.p2align 6
